# mixer B bias-table builder: the 5 per-thread iterations unrolled, the 5 dependent rel_table loads in flight together, one wait, then the 5 LDS writes
# baseline (speedup 1.0000x reference)
.LBB0_2753:
	v_readlane_b32 s28, v254, 51
	s_lshl_b32 s48, s46, 3
	v_sub_u32_e32 v54, 0xdf, v55
	v_lshl_add_u32 v53, v55, 2, s28
	v_mov_b32_e32 v57, v55
	s_mov_b32 s30, 0x66666667
	v_mul_hi_i32 v58, v57, s30
	v_lshrrev_b32_e32 v59, 31, v58
	v_ashrrev_i32_e32 v58, 7, v58
	v_add_u32_e32 v58, v58, v59
	s_movk_i32 s30, 0xfec0
	v_mad_i32_i24 v60, v58, s30, v57
	v_add_u32_e32 v59, 0xffffffa0, v60
	v_cmp_gt_u32_e32 vcc, s63, v59
	v_mov_b32_e32 v59, v224
	v_mov_b32_e32 v226, v224
	s_and_saveexec_b64 s[30:31], vcc
	s_cbranch_execz .Lmy_tb0_b
	v_mul_i32_i24_e32 v59, 0xfffffec0, v58
	s_movk_i32 s34, 0xd0
	v_sub_u32_e32 v59, v54, v59
	v_cmp_gt_u32_e32 vcc, s34, v60
	s_and_saveexec_b64 s[34:35], vcc
	s_cbranch_execz .Lmy_tb0_a
	v_cvt_f32_u32_e32 v59, v59
	s_mov_b32 s49, 0x800000
	v_mul_f32_e32 v59, 0x3d800000, v59
	v_cmp_gt_f32_e32 vcc, s49, v59
	s_mov_b32 s49, 0x3f317217
	s_nop 0
	v_cndmask_b32_e64 v60, 0, 32, vcc
	v_ldexp_f32 v59, v59, v60
	v_log_f32_e32 v59, v59
	v_cndmask_b32_e32 v60, 0, v220, vcc
	v_mul_f32_e32 v61, 0x3f317217, v59
	v_fma_f32 v61, v59, s49, -v61
	v_fmac_f32_e32 v61, 0x3377d1cf, v59
	s_mov_b32 s49, 0x7f800000
	v_fmac_f32_e32 v61, 0x3f317217, v59
	v_cmp_lt_f32_e64 vcc, |v59|, s49
	s_mov_b32 s49, 0x40051592
	s_nop 0
	v_cndmask_b32_e32 v59, v59, v61, vcc
	v_sub_f32_e32 v59, v59, v60
	v_div_scale_f32 v60, s[52:53], s49, s49, v59
	v_rcp_f32_e32 v61, v60
	v_div_scale_f32 v62, vcc, v59, s49, v59
	v_fma_f32 v63, -v60, v61, 1.0
	v_fmac_f32_e32 v61, v63, v61
	v_mul_f32_e32 v63, v62, v61
	v_fma_f32 v64, -v60, v63, v62
	v_fmac_f32_e32 v63, v64, v61
	v_fma_f32 v60, -v60, v63, v62
	v_div_fmas_f32 v60, v60, v61, v63
	v_div_fixup_f32 v59, v60, s49, v59
	v_mul_f32_e32 v59, 0x41800000, v59
	v_cvt_i32_f32_e32 v59, v59
	v_min_i32_e32 v59, 15, v59
	v_add_u32_e32 v59, 16, v59
.Lmy_tb0_a:
	s_or_b64 exec, exec, s[34:35]
	v_lshlrev_b32_e32 v59, 5, v59
	v_add3_u32 v58, v58, s48, v59
	v_ashrrev_i32_e32 v59, 31, v58
	v_lshl_add_u64 v[58:59], v[58:59], 2, s[6:7]
	global_load_dword v226, v[58:59], off
.Lmy_tb0_b:
	s_or_b64 exec, exec, s[30:31]
	v_add_u32_e32 v57, 0x200, v57
	v_add_u32_e32 v54, 0xfffffe00, v54
	s_mov_b32 s30, 0x66666667
	v_mul_hi_i32 v58, v57, s30
	v_lshrrev_b32_e32 v59, 31, v58
	v_ashrrev_i32_e32 v58, 7, v58
	v_add_u32_e32 v58, v58, v59
	s_movk_i32 s30, 0xfec0
	v_mad_i32_i24 v60, v58, s30, v57
	v_add_u32_e32 v59, 0xffffffa0, v60
	v_cmp_gt_u32_e32 vcc, s63, v59
	v_mov_b32_e32 v59, v224
	v_mov_b32_e32 v227, v224
	s_and_saveexec_b64 s[30:31], vcc
	s_cbranch_execz .Lmy_tb1_b
	v_mul_i32_i24_e32 v59, 0xfffffec0, v58
	s_movk_i32 s34, 0xd0
	v_sub_u32_e32 v59, v54, v59
	v_cmp_gt_u32_e32 vcc, s34, v60
	s_and_saveexec_b64 s[34:35], vcc
	s_cbranch_execz .Lmy_tb1_a
	v_cvt_f32_u32_e32 v59, v59
	s_mov_b32 s49, 0x800000
	v_mul_f32_e32 v59, 0x3d800000, v59
	v_cmp_gt_f32_e32 vcc, s49, v59
	s_mov_b32 s49, 0x3f317217
	s_nop 0
	v_cndmask_b32_e64 v60, 0, 32, vcc
	v_ldexp_f32 v59, v59, v60
	v_log_f32_e32 v59, v59
	v_cndmask_b32_e32 v60, 0, v220, vcc
	v_mul_f32_e32 v61, 0x3f317217, v59
	v_fma_f32 v61, v59, s49, -v61
	v_fmac_f32_e32 v61, 0x3377d1cf, v59
	s_mov_b32 s49, 0x7f800000
	v_fmac_f32_e32 v61, 0x3f317217, v59
	v_cmp_lt_f32_e64 vcc, |v59|, s49
	s_mov_b32 s49, 0x40051592
	s_nop 0
	v_cndmask_b32_e32 v59, v59, v61, vcc
	v_sub_f32_e32 v59, v59, v60
	v_div_scale_f32 v60, s[52:53], s49, s49, v59
	v_rcp_f32_e32 v61, v60
	v_div_scale_f32 v62, vcc, v59, s49, v59
	v_fma_f32 v63, -v60, v61, 1.0
	v_fmac_f32_e32 v61, v63, v61
	v_mul_f32_e32 v63, v62, v61
	v_fma_f32 v64, -v60, v63, v62
	v_fmac_f32_e32 v63, v64, v61
	v_fma_f32 v60, -v60, v63, v62
	v_div_fmas_f32 v60, v60, v61, v63
	v_div_fixup_f32 v59, v60, s49, v59
	v_mul_f32_e32 v59, 0x41800000, v59
	v_cvt_i32_f32_e32 v59, v59
	v_min_i32_e32 v59, 15, v59
	v_add_u32_e32 v59, 16, v59
.Lmy_tb1_a:
	s_or_b64 exec, exec, s[34:35]
	v_lshlrev_b32_e32 v59, 5, v59
	v_add3_u32 v58, v58, s48, v59
	v_ashrrev_i32_e32 v59, 31, v58
	v_lshl_add_u64 v[58:59], v[58:59], 2, s[6:7]
	global_load_dword v227, v[58:59], off
.Lmy_tb1_b:
	s_or_b64 exec, exec, s[30:31]
	v_add_u32_e32 v57, 0x200, v57
	v_add_u32_e32 v54, 0xfffffe00, v54
	s_mov_b32 s30, 0x66666667
	v_mul_hi_i32 v58, v57, s30
	v_lshrrev_b32_e32 v59, 31, v58
	v_ashrrev_i32_e32 v58, 7, v58
	v_add_u32_e32 v58, v58, v59
	s_movk_i32 s30, 0xfec0
	v_mad_i32_i24 v60, v58, s30, v57
	v_add_u32_e32 v59, 0xffffffa0, v60
	v_cmp_gt_u32_e32 vcc, s63, v59
	v_mov_b32_e32 v59, v224
	v_mov_b32_e32 v228, v224
	s_and_saveexec_b64 s[30:31], vcc
	s_cbranch_execz .Lmy_tb2_b
	v_mul_i32_i24_e32 v59, 0xfffffec0, v58
	s_movk_i32 s34, 0xd0
	v_sub_u32_e32 v59, v54, v59
	v_cmp_gt_u32_e32 vcc, s34, v60
	s_and_saveexec_b64 s[34:35], vcc
	s_cbranch_execz .Lmy_tb2_a
	v_cvt_f32_u32_e32 v59, v59
	s_mov_b32 s49, 0x800000
	v_mul_f32_e32 v59, 0x3d800000, v59
	v_cmp_gt_f32_e32 vcc, s49, v59
	s_mov_b32 s49, 0x3f317217
	s_nop 0
	v_cndmask_b32_e64 v60, 0, 32, vcc
	v_ldexp_f32 v59, v59, v60
	v_log_f32_e32 v59, v59
	v_cndmask_b32_e32 v60, 0, v220, vcc
	v_mul_f32_e32 v61, 0x3f317217, v59
	v_fma_f32 v61, v59, s49, -v61
	v_fmac_f32_e32 v61, 0x3377d1cf, v59
	s_mov_b32 s49, 0x7f800000
	v_fmac_f32_e32 v61, 0x3f317217, v59
	v_cmp_lt_f32_e64 vcc, |v59|, s49
	s_mov_b32 s49, 0x40051592
	s_nop 0
	v_cndmask_b32_e32 v59, v59, v61, vcc
	v_sub_f32_e32 v59, v59, v60
	v_div_scale_f32 v60, s[52:53], s49, s49, v59
	v_rcp_f32_e32 v61, v60
	v_div_scale_f32 v62, vcc, v59, s49, v59
	v_fma_f32 v63, -v60, v61, 1.0
	v_fmac_f32_e32 v61, v63, v61
	v_mul_f32_e32 v63, v62, v61
	v_fma_f32 v64, -v60, v63, v62
	v_fmac_f32_e32 v63, v64, v61
	v_fma_f32 v60, -v60, v63, v62
	v_div_fmas_f32 v60, v60, v61, v63
	v_div_fixup_f32 v59, v60, s49, v59
	v_mul_f32_e32 v59, 0x41800000, v59
	v_cvt_i32_f32_e32 v59, v59
	v_min_i32_e32 v59, 15, v59
	v_add_u32_e32 v59, 16, v59
.Lmy_tb2_a:
	s_or_b64 exec, exec, s[34:35]
	v_lshlrev_b32_e32 v59, 5, v59
	v_add3_u32 v58, v58, s48, v59
	v_ashrrev_i32_e32 v59, 31, v58
	v_lshl_add_u64 v[58:59], v[58:59], 2, s[6:7]
	global_load_dword v228, v[58:59], off
.Lmy_tb2_b:
	s_or_b64 exec, exec, s[30:31]
	v_add_u32_e32 v57, 0x200, v57
	v_add_u32_e32 v54, 0xfffffe00, v54
	s_mov_b32 s30, 0x66666667
	v_mul_hi_i32 v58, v57, s30
	v_lshrrev_b32_e32 v59, 31, v58
	v_ashrrev_i32_e32 v58, 7, v58
	v_add_u32_e32 v58, v58, v59
	s_movk_i32 s30, 0xfec0
	v_mad_i32_i24 v60, v58, s30, v57
	v_add_u32_e32 v59, 0xffffffa0, v60
	v_cmp_gt_u32_e32 vcc, s63, v59
	v_mov_b32_e32 v59, v224
	v_mov_b32_e32 v229, v224
	s_and_saveexec_b64 s[30:31], vcc
	s_cbranch_execz .Lmy_tb3_b
	v_mul_i32_i24_e32 v59, 0xfffffec0, v58
	s_movk_i32 s34, 0xd0
	v_sub_u32_e32 v59, v54, v59
	v_cmp_gt_u32_e32 vcc, s34, v60
	s_and_saveexec_b64 s[34:35], vcc
	s_cbranch_execz .Lmy_tb3_a
	v_cvt_f32_u32_e32 v59, v59
	s_mov_b32 s49, 0x800000
	v_mul_f32_e32 v59, 0x3d800000, v59
	v_cmp_gt_f32_e32 vcc, s49, v59
	s_mov_b32 s49, 0x3f317217
	s_nop 0
	v_cndmask_b32_e64 v60, 0, 32, vcc
	v_ldexp_f32 v59, v59, v60
	v_log_f32_e32 v59, v59
	v_cndmask_b32_e32 v60, 0, v220, vcc
	v_mul_f32_e32 v61, 0x3f317217, v59
	v_fma_f32 v61, v59, s49, -v61
	v_fmac_f32_e32 v61, 0x3377d1cf, v59
	s_mov_b32 s49, 0x7f800000
	v_fmac_f32_e32 v61, 0x3f317217, v59
	v_cmp_lt_f32_e64 vcc, |v59|, s49
	s_mov_b32 s49, 0x40051592
	s_nop 0
	v_cndmask_b32_e32 v59, v59, v61, vcc
	v_sub_f32_e32 v59, v59, v60
	v_div_scale_f32 v60, s[52:53], s49, s49, v59
	v_rcp_f32_e32 v61, v60
	v_div_scale_f32 v62, vcc, v59, s49, v59
	v_fma_f32 v63, -v60, v61, 1.0
	v_fmac_f32_e32 v61, v63, v61
	v_mul_f32_e32 v63, v62, v61
	v_fma_f32 v64, -v60, v63, v62
	v_fmac_f32_e32 v63, v64, v61
	v_fma_f32 v60, -v60, v63, v62
	v_div_fmas_f32 v60, v60, v61, v63
	v_div_fixup_f32 v59, v60, s49, v59
	v_mul_f32_e32 v59, 0x41800000, v59
	v_cvt_i32_f32_e32 v59, v59
	v_min_i32_e32 v59, 15, v59
	v_add_u32_e32 v59, 16, v59
.Lmy_tb3_a:
	s_or_b64 exec, exec, s[34:35]
	v_lshlrev_b32_e32 v59, 5, v59
	v_add3_u32 v58, v58, s48, v59
	v_ashrrev_i32_e32 v59, 31, v58
	v_lshl_add_u64 v[58:59], v[58:59], 2, s[6:7]
	global_load_dword v229, v[58:59], off
.Lmy_tb3_b:
	s_or_b64 exec, exec, s[30:31]
	v_add_u32_e32 v57, 0x200, v57
	v_add_u32_e32 v54, 0xfffffe00, v54
	s_mov_b32 s30, 0x66666667
	v_mul_hi_i32 v58, v57, s30
	v_lshrrev_b32_e32 v59, 31, v58
	v_ashrrev_i32_e32 v58, 7, v58
	v_add_u32_e32 v58, v58, v59
	s_movk_i32 s30, 0xfec0
	v_mad_i32_i24 v60, v58, s30, v57
	v_add_u32_e32 v59, 0xffffffa0, v60
	v_cmp_gt_u32_e32 vcc, s63, v59
	v_mov_b32_e32 v59, v224
	v_mov_b32_e32 v230, v224
	s_and_saveexec_b64 s[30:31], vcc
	s_cbranch_execz .Lmy_tb4_b
	v_mul_i32_i24_e32 v59, 0xfffffec0, v58
	s_movk_i32 s34, 0xd0
	v_sub_u32_e32 v59, v54, v59
	v_cmp_gt_u32_e32 vcc, s34, v60
	s_and_saveexec_b64 s[34:35], vcc
	s_cbranch_execz .Lmy_tb4_a
	v_cvt_f32_u32_e32 v59, v59
	s_mov_b32 s49, 0x800000
	v_mul_f32_e32 v59, 0x3d800000, v59
	v_cmp_gt_f32_e32 vcc, s49, v59
	s_mov_b32 s49, 0x3f317217
	s_nop 0
	v_cndmask_b32_e64 v60, 0, 32, vcc
	v_ldexp_f32 v59, v59, v60
	v_log_f32_e32 v59, v59
	v_cndmask_b32_e32 v60, 0, v220, vcc
	v_mul_f32_e32 v61, 0x3f317217, v59
	v_fma_f32 v61, v59, s49, -v61
	v_fmac_f32_e32 v61, 0x3377d1cf, v59
	s_mov_b32 s49, 0x7f800000
	v_fmac_f32_e32 v61, 0x3f317217, v59
	v_cmp_lt_f32_e64 vcc, |v59|, s49
	s_mov_b32 s49, 0x40051592
	s_nop 0
	v_cndmask_b32_e32 v59, v59, v61, vcc
	v_sub_f32_e32 v59, v59, v60
	v_div_scale_f32 v60, s[52:53], s49, s49, v59
	v_rcp_f32_e32 v61, v60
	v_div_scale_f32 v62, vcc, v59, s49, v59
	v_fma_f32 v63, -v60, v61, 1.0
	v_fmac_f32_e32 v61, v63, v61
	v_mul_f32_e32 v63, v62, v61
	v_fma_f32 v64, -v60, v63, v62
	v_fmac_f32_e32 v63, v64, v61
	v_fma_f32 v60, -v60, v63, v62
	v_div_fmas_f32 v60, v60, v61, v63
	v_div_fixup_f32 v59, v60, s49, v59
	v_mul_f32_e32 v59, 0x41800000, v59
	v_cvt_i32_f32_e32 v59, v59
	v_min_i32_e32 v59, 15, v59
	v_add_u32_e32 v59, 16, v59
.Lmy_tb4_a:
	s_or_b64 exec, exec, s[34:35]
	v_lshlrev_b32_e32 v59, 5, v59
	v_add3_u32 v58, v58, s48, v59
	v_ashrrev_i32_e32 v59, 31, v58
	v_lshl_add_u64 v[58:59], v[58:59], 2, s[6:7]
	global_load_dword v230, v[58:59], off
.Lmy_tb4_b:
	s_or_b64 exec, exec, s[30:31]
	v_add_u32_e32 v57, 0x200, v57
	v_add_u32_e32 v54, 0xfffffe00, v54
	s_waitcnt vmcnt(0)
	v_mul_f32_e32 v59, 0x3fb8aa3b, v226
	ds_write_b32 v53, v59
	v_mul_f32_e32 v59, 0x3fb8aa3b, v227
	ds_write_b32 v53, v59 offset:2048
	v_mul_f32_e32 v59, 0x3fb8aa3b, v228
	ds_write_b32 v53, v59 offset:4096
	v_mul_f32_e32 v59, 0x3fb8aa3b, v229
	ds_write_b32 v53, v59 offset:6144
	v_mul_f32_e32 v59, 0x3fb8aa3b, v230
	ds_write_b32 v53, v59 offset:8192
